# row phase RMS-norm reductions in registers: v_permlane32/16_swap for the cross-row steps and DPP row ops for the rest, replacing 12 ds_bpermute ladders per row
# speedup vs baseline: 1.0021x; 1.0021x over previous
.Lrows_o_loaded:
	s_waitcnt vmcnt(7)
	v_mov_b64_e32 v[34:35], v[104:105]
	s_waitcnt vmcnt(6)
	v_mov_b64_e32 v[70:71], v[106:107]
	v_lshlrev_b32_e32 v144, 1, v38
	v_and_b32_e32 v33, 0xffff0000, v34
	v_and_b32_e32 v95, 0xffff0000, v70
	v_lshlrev_b32_e32 v32, 16, v34
	v_mul_f32_e32 v72, v33, v33
	v_lshlrev_b32_e32 v94, 16, v70
	v_mul_f32_e32 v70, v95, v95
	v_lshlrev_b32_e32 v34, 16, v35
	v_fmac_f32_e32 v72, v32, v32
	v_lshlrev_b32_e32 v92, 16, v71
	v_fmac_f32_e32 v70, v94, v94
	v_and_b32_e32 v35, 0xffff0000, v35
	v_fmac_f32_e32 v72, v34, v34
	v_and_b32_e32 v93, 0xffff0000, v71
	v_fmac_f32_e32 v70, v92, v92
	v_fmac_f32_e32 v72, v35, v35
	v_fmac_f32_e32 v70, v93, v93
	v_add_f32_e32 v72, v72, v70
	s_waitcnt vmcnt(5)
	v_mov_b64_e32 v[70:71], v[108:109]
	v_and_b32_e32 v91, 0xffff0000, v70
	v_lshlrev_b32_e32 v90, 16, v70
	v_mul_f32_e32 v70, v91, v91
	v_lshlrev_b32_e32 v88, 16, v71
	v_fmac_f32_e32 v70, v90, v90
	v_and_b32_e32 v89, 0xffff0000, v71
	v_fmac_f32_e32 v70, v88, v88
	v_fmac_f32_e32 v70, v89, v89
	v_add_f32_e32 v72, v72, v70
	s_waitcnt vmcnt(4)
	v_mov_b64_e32 v[70:71], v[110:111]
	v_and_b32_e32 v87, 0xffff0000, v70
	v_lshlrev_b32_e32 v86, 16, v70
	v_mul_f32_e32 v70, v87, v87
	v_lshlrev_b32_e32 v84, 16, v71
	v_fmac_f32_e32 v70, v86, v86
	v_and_b32_e32 v85, 0xffff0000, v71
	v_fmac_f32_e32 v70, v84, v84
	v_fmac_f32_e32 v70, v85, v85
	v_add_f32_e32 v74, v72, v70
	s_waitcnt vmcnt(3)
	v_mov_b64_e32 v[70:71], v[112:113]
	s_waitcnt vmcnt(2)
	v_mov_b64_e32 v[72:73], v[114:115]
	v_and_b32_e32 v82, 0xffff0000, v70
	v_lshlrev_b32_e32 v81, 16, v72
	v_and_b32_e32 v83, 0xffff0000, v72
	v_lshlrev_b32_e32 v79, 16, v73
	v_and_b32_e32 v77, 0xffff0000, v73
	s_waitcnt vmcnt(1)
	v_mov_b64_e32 v[96:97], v[116:117]
	s_waitcnt vmcnt(0)
	v_mov_b64_e32 v[72:73], v[118:119]
	v_lshlrev_b32_e32 v80, 16, v70
	v_lshlrev_b32_e32 v78, 16, v71
	v_and_b32_e32 v76, 0xffff0000, v71
	v_pk_mul_f32 v[70:71], v[82:83], v[82:83]
	v_and_b32_e32 v68, 0xffff0000, v96
	v_pk_fma_f32 v[70:71], v[80:81], v[80:81], v[70:71]
	v_and_b32_e32 v69, 0xffff0000, v72
	v_pk_fma_f32 v[70:71], v[78:79], v[78:79], v[70:71]
	v_lshlrev_b32_e32 v75, 16, v73
	v_pk_fma_f32 v[70:71], v[76:77], v[76:77], v[70:71]
	v_and_b32_e32 v73, 0xffff0000, v73
	v_add_f32_e32 v70, v74, v70
	v_add_f32_e32 v98, v70, v71
	v_lshlrev_b32_e32 v71, 16, v72
	v_lshlrev_b32_e32 v70, 16, v96
	v_lshlrev_b32_e32 v74, 16, v97
	v_and_b32_e32 v72, 0xffff0000, v97
	v_pk_mul_f32 v[96:97], v[68:69], v[68:69]
	s_nop 0
	v_pk_fma_f32 v[96:97], v[70:71], v[70:71], v[96:97]
	s_nop 0
	v_pk_fma_f32 v[96:97], v[74:75], v[74:75], v[96:97]
	s_nop 0
	v_pk_fma_f32 v[96:97], v[72:73], v[72:73], v[96:97]
	s_nop 0
	v_add_f32_e32 v96, v98, v96
	v_add_f32_e32 v96, v96, v97
	v_mov_b32_e32 v98, v96
	s_nop 1
	v_permlane32_swap_b32_e32 v98, v96
	s_nop 1
	v_add_f32_e32 v96, v96, v98
	v_mov_b32_e32 v98, v96
	s_nop 1
	v_permlane16_swap_b32_e32 v98, v96
	s_nop 1
	v_add_f32_e32 v96, v96, v98
	s_nop 1
	v_add_f32_dpp v96, v96, v96 row_mirror row_mask:0xf bank_mask:0xf
	s_nop 1
	v_add_f32_dpp v96, v96, v96 row_half_mirror row_mask:0xf bank_mask:0xf
	s_nop 1
	v_add_f32_dpp v96, v96, v96 quad_perm:[2,3,0,1] row_mask:0xf bank_mask:0xf
	s_nop 1
	v_add_f32_dpp v96, v96, v96 quad_perm:[1,0,3,2] row_mask:0xf bank_mask:0xf
	ds_read_b128 v[98:101], v40
	v_fmamk_f32 v96, v96, 0x3a000000, v176
	v_cmp_gt_f32_e32 vcc, s72, v96
	v_mul_f32_e32 v97, 0x4b800000, v96
	s_nop 0
	v_cndmask_b32_e32 v96, v96, v97, vcc
	v_rsq_f32_e32 v96, v96
	s_nop 0
	v_mul_f32_e32 v97, 0x45800000, v96
	v_cndmask_b32_e32 v96, v96, v97, vcc
	v_pk_mul_f32 v[32:33], v[32:33], v[96:97] op_sel_hi:[1,0]
	v_pk_mul_f32 v[34:35], v[34:35], v[96:97] op_sel_hi:[1,0]
	s_waitcnt lgkmcnt(0)
	v_pk_fma_f32 v[32:33], v[98:99], v[32:33], v[28:29]
	v_mov_b64_e32 v[28:29], s[2:3]
	v_pk_fma_f32 v[34:35], v[100:101], v[34:35], v[30:31]
	v_mad_i64_i32 v[98:99], s[0:1], v66, s70, v[28:29]
	s_mov_b64 s[0:1], -1
	s_and_b64 vcc, exec, s[36:37]
	v_mov_b32_e32 v31, v35
	v_mov_b32_e32 v30, v34
	v_mov_b32_e32 v29, v33
	v_mov_b32_e32 v28, v32
	s_cbranch_vccz .LBB0_442
	v_cvt_pk_bf16_f32 v30, v32, v33
	v_cvt_pk_bf16_f32 v31, v34, v35
	v_lshl_add_u64 v[28:29], v[98:99], 0, v[144:145]
	global_store_dwordx2 v[28:29], v[30:31], off
	v_lshlrev_b32_e32 v28, 16, v30
	v_and_b32_e32 v29, 0xffff0000, v30
	v_lshlrev_b32_e32 v30, 16, v31
	v_and_b32_e32 v31, 0xffff0000, v31
	s_mov_b64 s[0:1], 0

.LBB0_472:
	s_and_b64 vcc, exec, s[40:41]
	s_cbranch_vccnz .LBB0_434
	s_waitcnt vmcnt(7)
	v_mul_f32_e32 v32, v29, v29
	s_waitcnt vmcnt(6)
	v_mul_f32_e32 v33, v25, v25
	v_fmac_f32_e32 v32, v28, v28
	v_fmac_f32_e32 v33, v24, v24
	v_fmac_f32_e32 v32, v30, v30
	v_fmac_f32_e32 v33, v26, v26
	v_fmac_f32_e32 v32, v31, v31
	v_fmac_f32_e32 v33, v27, v27
	v_add_f32_e32 v32, v32, v33
	s_waitcnt vmcnt(5)
	v_mul_f32_e32 v33, v21, v21
	v_fmac_f32_e32 v33, v20, v20
	v_fmac_f32_e32 v33, v22, v22
	v_fmac_f32_e32 v33, v23, v23
	v_add_f32_e32 v32, v33, v32
	s_waitcnt vmcnt(4)
	v_mul_f32_e32 v33, v17, v17
	s_waitcnt vmcnt(2)
	v_pk_mul_f32 v[76:77], v[8:9], v[8:9]
	v_pk_mul_f32 v[78:79], v[12:13], v[12:13]
	v_fmac_f32_e32 v33, v16, v16
	v_pk_mul_f32 v[72:73], v[10:11], v[10:11]
	v_pk_mul_f32 v[74:75], v[14:15], v[14:15]
	v_mov_b32_e32 v80, v76
	v_mov_b32_e32 v81, v78
	v_mov_b32_e32 v78, v77
	v_fmac_f32_e32 v33, v18, v18
	v_pk_add_f32 v[76:77], v[80:81], v[78:79]
	v_mov_b32_e32 v78, v72
	v_mov_b32_e32 v79, v74
	v_fmac_f32_e32 v33, v19, v19
	v_pk_add_f32 v[76:77], v[78:79], v[76:77]
	v_mov_b32_e32 v74, v73
	v_add_f32_e32 v67, v33, v32
	v_pk_add_f32 v[72:73], v[74:75], v[76:77]
	s_waitcnt vmcnt(1)
	v_pk_mul_f32 v[68:69], v[4:5], v[4:5]
	s_waitcnt vmcnt(0)
	v_pk_mul_f32 v[70:71], v[0:1], v[0:1]
	v_add_f32_e32 v67, v73, v67
	v_pk_mul_f32 v[32:33], v[6:7], v[6:7]
	v_pk_mul_f32 v[34:35], v[2:3], v[2:3]
	v_add_f32_e32 v67, v72, v67
	v_mov_b32_e32 v72, v70
	v_mov_b32_e32 v73, v68
	v_mov_b32_e32 v68, v71
	v_pk_add_f32 v[68:69], v[72:73], v[68:69]
	v_mov_b32_e32 v70, v34
	v_mov_b32_e32 v71, v32
	v_pk_add_f32 v[68:69], v[70:71], v[68:69]
	v_mov_b32_e32 v32, v35
	v_pk_add_f32 v[32:33], v[32:33], v[68:69]
	v_add_f32_e32 v33, v33, v67
	v_add_f32_e32 v32, v32, v33
	ds_read_b128 v[68:71], v40 offset:8192
	ds_read_b128 v[72:75], v40 offset:16384
	v_mov_b32_e32 v34, v32
	s_nop 1
	v_permlane32_swap_b32_e32 v34, v32
	s_nop 1
	v_add_f32_e32 v32, v32, v34
	v_mov_b32_e32 v34, v32
	s_nop 1
	v_permlane16_swap_b32_e32 v34, v32
	s_nop 1
	v_add_f32_e32 v32, v32, v34
	s_nop 1
	v_add_f32_dpp v32, v32, v32 row_mirror row_mask:0xf bank_mask:0xf
	s_nop 1
	v_add_f32_dpp v32, v32, v32 row_half_mirror row_mask:0xf bank_mask:0xf
	s_nop 1
	v_add_f32_dpp v32, v32, v32 quad_perm:[2,3,0,1] row_mask:0xf bank_mask:0xf
	s_nop 1
	v_add_f32_dpp v32, v32, v32 quad_perm:[1,0,3,2] row_mask:0xf bank_mask:0xf
	s_waitcnt lgkmcnt(0)
	v_fmamk_f32 v32, v32, 0x3a000000, v176
	v_cmp_gt_f32_e32 vcc, s72, v32
	v_mul_f32_e32 v33, 0x4b800000, v32
	s_nop 0
	v_cndmask_b32_e32 v32, v32, v33, vcc
	v_rsq_f32_e32 v32, v32
	s_nop 0
	v_mul_f32_e32 v33, 0x45800000, v32
	v_cndmask_b32_e32 v32, v32, v33, vcc
	v_pk_mul_f32 v[28:29], v[28:29], v[32:33] op_sel_hi:[1,0]
	v_pk_mul_f32 v[30:31], v[30:31], v[32:33] op_sel_hi:[1,0]
	v_pk_fma_f32 v[28:29], v[68:69], v[28:29], v[72:73]
	v_pk_fma_f32 v[30:31], v[70:71], v[30:31], v[74:75]
	v_cvt_pk_bf16_f32 v34, v28, v29
	v_mad_i64_i32 v[28:29], s[0:1], v66, s70, v[64:65]
	v_cvt_pk_bf16_f32 v35, v30, v31
	global_store_dwordx2 v[28:29], v[34:35], off
	ds_read_b128 v[66:69], v40 offset:9216
	ds_read_b128 v[70:73], v40 offset:17408
	v_pk_mul_f32 v[24:25], v[24:25], v[32:33] op_sel_hi:[1,0]
	v_pk_mul_f32 v[26:27], v[26:27], v[32:33] op_sel_hi:[1,0]
	v_pk_mul_f32 v[20:21], v[20:21], v[32:33] op_sel_hi:[1,0]
	v_pk_mul_f32 v[22:23], v[22:23], v[32:33] op_sel_hi:[1,0]
	s_waitcnt lgkmcnt(0)
	v_pk_fma_f32 v[24:25], v[66:67], v[24:25], v[70:71]
	v_pk_fma_f32 v[26:27], v[68:69], v[26:27], v[72:73]
	v_cvt_pk_bf16_f32 v24, v24, v25
	v_pk_mul_f32 v[16:17], v[16:17], v[32:33] op_sel_hi:[1,0]
	v_cvt_pk_bf16_f32 v25, v26, v27
	global_store_dwordx2 v[28:29], v[24:25], off offset:512
	ds_read_b128 v[24:27], v40 offset:10240
	ds_read_b128 v[66:69], v40 offset:18432
	v_pk_mul_f32 v[18:19], v[18:19], v[32:33] op_sel_hi:[1,0]
	v_pk_mul_f32 v[12:13], v[12:13], v[32:33] op_sel_hi:[1,0]
	v_pk_mul_f32 v[14:15], v[14:15], v[32:33] op_sel_hi:[1,0]
	v_pk_mul_f32 v[8:9], v[8:9], v[32:33] op_sel_hi:[1,0]
	s_waitcnt lgkmcnt(0)
	v_pk_fma_f32 v[20:21], v[24:25], v[20:21], v[66:67]
	v_pk_fma_f32 v[22:23], v[26:27], v[22:23], v[68:69]
	v_cvt_pk_bf16_f32 v20, v20, v21
	v_pk_mul_f32 v[10:11], v[10:11], v[32:33] op_sel_hi:[1,0]
	v_cvt_pk_bf16_f32 v21, v22, v23
	global_store_dwordx2 v[28:29], v[20:21], off offset:1024
	ds_read_b128 v[20:23], v40 offset:11264
	ds_read_b128 v[24:27], v40 offset:19456
	v_pk_mul_f32 v[4:5], v[4:5], v[32:33] op_sel_hi:[1,0]
	v_pk_mul_f32 v[6:7], v[6:7], v[32:33] op_sel_hi:[1,0]
	v_pk_mul_f32 v[0:1], v[0:1], v[32:33] op_sel_hi:[1,0]
	v_pk_mul_f32 v[2:3], v[2:3], v[32:33] op_sel_hi:[1,0]
	s_waitcnt lgkmcnt(0)
	v_pk_fma_f32 v[16:17], v[16:17], v[20:21], v[24:25]
	v_pk_fma_f32 v[18:19], v[18:19], v[22:23], v[26:27]
	v_cvt_pk_bf16_f32 v16, v16, v17
	s_nop 0
	v_cvt_pk_bf16_f32 v17, v18, v19
	global_store_dwordx2 v[28:29], v[16:17], off offset:1536
	ds_read_b128 v[16:19], v40 offset:12288
	ds_read_b128 v[20:23], v40 offset:20480
	s_waitcnt lgkmcnt(0)
	v_pk_fma_f32 v[12:13], v[12:13], v[16:17], v[20:21]
	v_pk_fma_f32 v[14:15], v[14:15], v[18:19], v[22:23]
	v_cvt_pk_bf16_f32 v12, v12, v13
	s_nop 0
	v_cvt_pk_bf16_f32 v13, v14, v15
	global_store_dwordx2 v[28:29], v[12:13], off offset:2048
	ds_read_b128 v[12:15], v40 offset:13312
	ds_read_b128 v[16:19], v40 offset:21504
	s_waitcnt lgkmcnt(0)
	v_pk_fma_f32 v[8:9], v[8:9], v[12:13], v[16:17]
	v_pk_fma_f32 v[10:11], v[10:11], v[14:15], v[18:19]
	v_cvt_pk_bf16_f32 v8, v8, v9
	s_nop 0
	v_cvt_pk_bf16_f32 v9, v10, v11
	global_store_dwordx2 v[28:29], v[8:9], off offset:2560
	ds_read_b128 v[8:11], v40 offset:14336
	ds_read_b128 v[12:15], v40 offset:22528
	s_waitcnt lgkmcnt(0)
	v_pk_fma_f32 v[4:5], v[4:5], v[8:9], v[12:13]
	v_pk_fma_f32 v[6:7], v[6:7], v[10:11], v[14:15]
	v_cvt_pk_bf16_f32 v4, v4, v5
	s_nop 0
	v_cvt_pk_bf16_f32 v5, v6, v7
	global_store_dwordx2 v[28:29], v[4:5], off offset:3072
	ds_read_b128 v[4:7], v40 offset:15360
	ds_read_b128 v[8:11], v40 offset:23552
	s_waitcnt lgkmcnt(0)
	v_pk_fma_f32 v[0:1], v[0:1], v[4:5], v[8:9]
	v_pk_fma_f32 v[2:3], v[2:3], v[6:7], v[10:11]
	v_cvt_pk_bf16_f32 v0, v0, v1
	s_nop 0
	v_cvt_pk_bf16_f32 v1, v2, v3
	global_store_dwordx2 v[28:29], v[0:1], off offset:3584
	s_branch .LBB0_434
